# P4 epilogue rewritten: all rms/XH loads issued up front, counted vmcnt, streamed write-through stores, batched row-stat reductions
# speedup vs baseline: 1.0270x; 1.0140x over previous
.LBB0_537:
	s_or_b64 exec, exec, s[0:1]
	s_and_b64 s[0:1], s[36:37], exec
	s_cselect_b32 s28, 16, 0x1000
	s_add_u32 s64, s76, 0x13d00000
	s_addc_u32 s65, s77, 0
	s_bfe_u32 s68, s96, 0x20006
	s_mul_i32 s0, s68, 0x3700
	s_add_i32 s71, s0, 0
	s_and_b32 s0, s96, 0xffffff00
	s_lshr_b32 s74, s96, 8
	s_add_i32 s84, s0, 0
	s_lshl_b32 s11, s74, 5
	s_add_i32 s80, s84, 0x12600
	s_cmpk_lt_u32 s96, 0x540
	v_readlane_b32 s20, v255, 31
	s_cselect_b64 s[40:41], -1, 0
	s_add_i32 s12, s20, -4
	s_lshl_b32 s13, s12, 2
	s_lshl_b32 s22, s12, 10
	s_cmpk_lt_u32 s96, 0x440
	s_cselect_b64 s[42:43], -1, 0
	s_lshl_b32 s66, s20, 10
	s_cmpk_lt_u32 s96, 0x340
	s_cselect_b64 s[46:47], -1, 0
	s_add_i32 s14, s20, 4
	s_lshl_b32 s15, s14, 2
	s_lshl_b32 s23, s14, 10
	s_cmpk_lt_u32 s96, 0x240
	s_cselect_b64 s[48:49], -1, 0
	s_add_i32 s16, s20, 8
	s_lshl_b32 s17, s16, 2
	s_lshl_b32 s24, s16, 10
	s_cmp_eq_u32 s20, 4
	s_cselect_b64 s[50:51], -1, 0
	s_cmp_eq_u32 s20, 2
	s_mov_b32 s0, 0xfc00000
	s_cselect_b32 s38, s0, 0x13d00000
	s_add_u32 s8, s76, s6
	s_addc_u32 s9, s77, 0
	s_mul_i32 s0, s20, 0x2400
	s_add_i32 s1, 0, 0x1a900
	s_add_i32 s81, s1, s0
	s_lshl_b32 s0, s74, 7
	s_add_i32 s83, s0, 0
	s_add_i32 s82, s81, 0x2000
	s_add_i32 s83, s83, 0x14800
	s_add_i32 s84, s84, 0x12400
	s_lshl_b32 s29, s20, 5
	s_add_u32 s6, s64, s6
	s_addc_u32 s7, s65, 0
	s_lshl_b32 s85, s33, 10
	s_add_u32 s18, s76, 0x10000
	v_writelane_b32 v255, s96, 33
	s_addc_u32 s19, s77, 0
	v_lshl_or_b32 v11, s68, 4, v9
	v_writelane_b32 v255, s18, 34
	v_add_u32_e32 v25, 1, v11
	v_lshlrev_b32_e32 v27, 3, v38
	v_writelane_b32 v255, s19, 35
	v_lshlrev_b32_e32 v10, 7, v25
	v_and_b32_e32 v22, 8, v27
	s_add_i32 s0, 0, 0x1cd00
	s_add_i32 s18, 0, 0x1f100
	v_add3_u32 v91, s1, v10, v22
	v_add3_u32 v92, s0, v10, v22
	v_add3_u32 v93, s18, v10, v22
	v_lshlrev_b32_e32 v10, 8, v25
	s_add_i32 s19, 0, 0x23900
	v_add3_u32 v28, s19, v10, v22
	v_lshlrev_b32_e32 v10, 7, v11
	v_add3_u32 v94, s1, v10, v22
	v_add3_u32 v95, s0, v10, v22
	v_add3_u32 v96, s18, v10, v22
	v_lshlrev_b32_e32 v10, 8, v11
	v_add3_u32 v29, s19, v10, v22
	v_add_u32_e32 v10, 1, v89
	s_add_i32 s19, 0, 0x21500
	v_lshl_add_u32 v32, v10, 7, s19
	v_xor_b32_e32 v10, v10, v39
	v_lshlrev_b32_e32 v10, 4, v10
	v_and_b32_e32 v33, 0x70, v10
	v_lshlrev_b32_e32 v10, 7, v89
	v_add_u32_e32 v34, s19, v10
	s_add_i32 s19, 0, 0x12800
	s_cmp_lg_u32 s12, 16
	v_add_u32_e32 v36, s19, v10
	v_or_b32_e32 v10, s13, v38
	s_cselect_b64 vcc, -1, 0
	v_xor_b32_e32 v22, v89, v39
	v_cndmask_b32_e32 v98, 64, v10, vcc
	v_bitop3_b32 v10, v38, v39, s13 bitop3:0x36
	v_lshlrev_b32_e32 v22, 4, v22
	v_and_or_b32 v10, v10, 7, v41
	v_and_b32_e32 v35, 0x70, v22
	v_lshlrev_b32_e32 v22, 4, v10
	v_mov_b32_e32 v10, 0
	v_mov_b32_e32 v23, v10
	s_cmp_lg_u32 s20, 16
	v_lshl_add_u64 v[48:49], s[4:5], 0, v[22:23]
	v_or_b32_e32 v22, s3, v38
	s_cselect_b64 vcc, -1, 0
	v_cndmask_b32_e32 v99, 64, v22, vcc
	v_bitop3_b32 v22, v38, v39, s3 bitop3:0x36
	v_and_or_b32 v22, v22, 7, v41
	v_lshlrev_b32_e32 v22, 4, v22
	s_cmp_lg_u32 s14, 16
	v_lshl_add_u64 v[50:51], s[4:5], 0, v[22:23]
	v_or_b32_e32 v22, s15, v38
	s_cselect_b64 vcc, -1, 0
	v_cndmask_b32_e32 v100, 64, v22, vcc
	v_bitop3_b32 v22, v38, v39, s15 bitop3:0x36
	v_and_or_b32 v22, v22, 7, v41
	v_lshlrev_b32_e32 v22, 4, v22
	s_cmp_lg_u32 s16, 16
	v_lshl_add_u64 v[52:53], s[4:5], 0, v[22:23]
	v_or_b32_e32 v22, s17, v38
	s_cselect_b64 vcc, -1, 0
	v_cndmask_b32_e32 v101, 64, v22, vcc
	v_bitop3_b32 v22, v38, v39, s17 bitop3:0x36
	v_and_or_b32 v22, v22, 7, v41
	v_lshlrev_b32_e32 v22, 4, v22
	v_lshl_add_u64 v[54:55], s[4:5], 0, v[22:23]
	v_xor_b32_e32 v22, v38, v20
	s_movk_i32 s10, 0x3700
	v_or_b32_e32 v22, v22, v41
	v_lshlrev_b32_e32 v41, 5, v9
	v_lshrrev_b32_e32 v45, 7, v42
	v_cmp_gt_u32_e64 s[0:1], 16, v40
	v_or_b32_e32 v103, v27, v41
	v_lshl_add_u32 v104, v40, 2, s71
	v_add_u32_e32 v40, s71, v41
	v_lshrrev_b32_e32 v41, 2, v9
	v_mul_lo_u32 v45, v45, s10
	v_or_b32_e32 v41, v90, v41
	v_add_u32_e32 v67, 0, v45
	v_bfe_u32 v45, v42, 3, 4
	v_mul_u32_u24_e32 v41, 0x48, v41
	v_and_b32_e32 v21, 12, v21
	v_mul_u32_u24_e32 v45, 0x48, v45
	v_or_b32_e32 v24, s11, v90
	v_add_lshl_u32 v105, v21, v41, 1
	v_lshl_or_b32 v21, v89, 6, v8
	v_add_lshl_u32 v8, v45, v8, 1
	v_mov_b32_e32 v45, v10
	v_and_b32_e32 v26, 7, v25
	v_lshl_add_u64 v[60:61], s[6:7], 0, v[44:45]
	v_cmp_eq_u32_e64 s[6:7], 0, v42
	v_lshrrev_b32_e32 v42, 3, v24
	v_and_b32_e32 v62, 8, v42
	v_bitop3_b32 v63, v42, v26, 5 bitop3:0x6c
	v_or_b32_e32 v63, v63, v62
	v_lshlrev_b32_e32 v68, 4, v63
	v_add_u32_e32 v63, 64, v24
	v_bitop3_b32 v45, v42, v25, 7 bitop3:0x78
	v_lshrrev_b32_e32 v64, 3, v63
	v_xor_b32_e32 v69, v42, v20
	v_bitop3_b32 v42, v42, v20, 5 bitop3:0x6c
	v_and_b32_e32 v65, 8, v64
	v_or_b32_e32 v42, v42, v62
	v_bitop3_b32 v62, v64, v20, 5 bitop3:0x6c
	v_or_b32_e32 v62, v62, v65
	v_lshlrev_b32_e32 v108, 4, v69
	v_lshlrev_b32_e32 v69, 4, v62
	v_or_b32_e32 v62, 16, v24
	v_lshlrev_b32_e32 v22, 4, v22
	v_lshlrev_b32_e32 v71, 1, v63
	v_lshrrev_b32_e32 v63, 3, v62
	v_lshl_add_u64 v[56:57], s[4:5], 0, v[22:23]
	v_xor_b32_e32 v22, v88, v20
	v_bitop3_b32 v26, v64, v26, 5 bitop3:0x6c
	v_bitop3_b32 v64, v63, v25, 7 bitop3:0x78
	v_lshlrev_b32_e32 v22, 4, v22
	v_or_b32_e32 v26, v26, v65
	v_lshlrev_b32_e32 v111, 4, v64
	v_and_b32_e32 v64, 8, v63
	v_bitop3_b32 v65, v63, v25, 7 bitop3:0x28
	s_movk_i32 s18, 0x48
	v_lshl_add_u64 v[58:59], s[8:9], 0, v[22:23]
	v_or_b32_e32 v23, s11, v9
	v_or_b32_e32 v65, v65, v64
	v_mul_u32_u24_e32 v30, 0x48, v11
	v_mul_u32_u24_e32 v31, 0x48, v9
	v_lshlrev_b32_e32 v97, 2, v11
	v_or_b32_e32 v22, 16, v90
	v_lshlrev_b32_e32 v72, 4, v65
	v_add_u32_e32 v65, 0x50, v24
	v_mul_lo_u32 v23, v23, s18
	v_mad_u32_u24 v11, v11, s18, 32
	v_lshlrev_b32_e32 v70, 1, v24
	v_add_lshl_u32 v109, v24, v30, 1
	v_add_lshl_u32 v110, v24, v31, 1
	v_lshrrev_b32_e32 v73, 3, v65
	v_xor_b32_e32 v75, v63, v20
	v_bitop3_b32 v63, v63, v20, 7 bitop3:0x6c
	v_add_lshl_u32 v113, v62, v30, 1
	v_add_lshl_u32 v115, v30, v90, 1
	v_add_lshl_u32 v116, v22, v30, 1
	v_add_u32_e32 v30, 0x480, v23
	v_add_lshl_u32 v119, v11, v90, 1
	v_add_lshl_u32 v120, v11, v22, 1
	v_or_b32_e32 v11, 32, v90
	v_lshlrev_b32_e32 v123, 2, v24
	v_or_b32_e32 v24, 1, v90
	v_cmp_eq_u32_e32 vcc, v90, v9
	v_lshlrev_b32_e32 v106, 5, v20
	v_and_b32_e32 v74, 8, v73
	v_bitop3_b32 v25, v73, v25, 7 bitop3:0x28
	v_or_b32_e32 v63, v63, v64
	v_bitop3_b32 v20, v73, v20, 7 bitop3:0x6c
	v_lshlrev_b32_e32 v73, 1, v62
	v_add_lshl_u32 v114, v62, v31, 1
	v_add_lshl_u32 v118, v30, v90, 1
	v_add_lshl_u32 v122, v11, v30, 1
	v_lshlrev_b32_e32 v124, 2, v62
	v_or_b32_e32 v30, 2, v90
	v_cndmask_b32_e64 v62, 0, 1.0, vcc
	v_cmp_eq_u32_e32 vcc, v24, v9
	v_lshlrev_b32_e32 v112, 4, v75
	v_lshlrev_b32_e32 v75, 4, v63
	v_add_lshl_u32 v117, v90, v23, 1
	v_add_lshl_u32 v121, v11, v23, 1
	v_add_lshl_u32 v125, v90, v31, 1
	v_add_lshl_u32 v23, v11, v31, 1
	v_or_b32_e32 v31, 3, v90
	v_cndmask_b32_e64 v63, 0, 1.0, vcc
	v_cmp_eq_u32_e32 vcc, v30, v9
	v_cmp_eq_u32_e64 s[4:5], 0, v9
	v_mad_u32_u24 v37, v9, s18, 16
	v_cmp_lt_u32_e64 s[8:9], v90, v9
	v_cmp_gt_u32_e64 s[10:11], v90, v9
	v_cmp_lt_u32_e64 s[12:13], v24, v9
	v_cmp_lt_u32_e64 s[14:15], v30, v9
	v_cmp_gt_u32_e64 s[16:17], v30, v9
	v_cmp_lt_u32_e64 s[18:19], v31, v9
	v_cmp_gt_u32_e64 s[20:21], v31, v9
	v_cndmask_b32_e64 v64, 0, 1.0, vcc
	v_cmp_eq_u32_e32 vcc, v31, v9
	v_lshlrev_b32_e32 v9, 2, v9
	v_lshl_add_u32 v24, v38, 10, s97
	s_mov_b32 s3, 0xdc00
	v_add3_u32 v126, v24, v9, s3
	v_and_b32_e32 v9, 3, v39
	s_movk_i32 s25, 0x2400
	v_lshlrev_b32_e32 v43, 2, v21
	v_lshlrev_b32_e32 v21, 1, v21
	v_lshl_or_b32 v9, v9, 3, s29
	v_lshlrev_b32_e32 v24, 1, v41
	s_waitcnt lgkmcnt(0)
	s_barrier
	v_lshlrev_b32_e32 v66, 2, v89
	v_or_b32_e32 v25, v25, v74
	v_or_b32_e32 v20, v20, v74
	v_add3_u32 v128, v9, v24, s25
	v_mov_b32_e32 v9, 0x3540
	v_add_u32_e32 v151, v67, v8
	v_add_u32_e32 v8, 0, v21
	s_mov_b32 s39, 0
	v_and_b32_e32 v102, 48, v39
	v_lshlrev_b32_e32 v26, 4, v26
	v_lshlrev_b32_e32 v42, 4, v42
	v_lshlrev_b32_e32 v25, 4, v25
	v_lshlrev_b32_e32 v20, 4, v20
	v_lshlrev_b32_e32 v74, 1, v65
	v_add_lshl_u32 v22, v37, v90, 1
	v_add_lshl_u32 v11, v11, v37, 1
	v_writelane_b32 v255, s97, 32
	v_lshl_or_b32 v129, v38, 4, v9
	s_add_i32 s3, 0, 0x15c00
	s_add_i32 s88, s22, 0
	s_add_i32 s89, s23, 0
	s_add_i32 s90, s24, 0
	v_add_u32_e32 v9, 0, v66
	v_add_u32_e32 v152, 0x12800, v8
	v_mbcnt_lo_u32_b32 v8, -1, 0
	s_mov_b64 s[52:53], s[38:39]
	v_add_u32_e32 v107, s70, v89
	v_lshlrev_b32_e32 v45, 4, v45
	v_cndmask_b32_e64 v65, 0, 1.0, vcc
	v_add_u32_e32 v127, 0x2d00, v103
	v_writelane_b32 v255, s29, 44
	v_or_b32_e32 v130, 0x3500, v102
	v_add_u32_e32 v131, v28, v68
	v_add_u32_e32 v132, v28, v26
	v_add_u32_e32 v133, v29, v42
	v_add_u32_e32 v134, v29, v69
	v_add_u32_e32 v135, s3, v70
	v_add_u32_e32 v136, s3, v71
	s_mov_b32 s86, 0x4038aa3b
	s_add_i32 s67, 0, 0x10000
	v_add_u32_e32 v137, v28, v72
	v_add_u32_e32 v138, v28, v25
	v_add_u32_e32 v139, v29, v75
	v_add_u32_e32 v140, v29, v20
	v_add_u32_e32 v141, s3, v73
	v_add_u32_e32 v142, s3, v74
	v_add_u32_e32 v143, v32, v33
	v_add_u32_e32 v145, v34, v35
	s_mov_b32 s87, 0xbfb8aa3b
	v_add_u32_e32 v146, v36, v44
	s_add_i32 s88, s88, 0x23900
	s_add_i32 s89, s89, 0x23900
	s_add_i32 s90, s90, 0x23900
	s_add_i32 s91, 0, 0x27900
	s_add_i32 s92, s81, 0x400
	s_add_i32 s93, s81, 0x800
	s_add_i32 s94, s81, 0xc00
	s_add_i32 s95, s81, 0x1400
	s_add_i32 s96, s81, 0x1800
	s_add_i32 s97, s81, 0x1c00
	s_add_i32 s3, 0, 0x16100
	s_add_i32 s69, 0, 0x18500
	v_mov_b32_e32 v147, 0xbf92477c
	v_add_u32_e32 v148, v40, v27
	s_xor_b64 s[54:55], s[26:27], -1
	v_add_u32_e32 v149, 0, v43
	v_add_u32_e32 v150, 0x12400, v9
	v_mov_b32_e32 v153, 0x3a27c5ac
	v_mbcnt_hi_u32_b32 v144, -1, v8
	v_add_u32_e32 v154, s71, v22
	v_add_u32_e32 v155, s71, v23
	v_add_u32_e32 v156, s71, v11
	s_mov_b32 s33, s28
	s_mov_b32 s29, 0
	v_add_u32_e32 v231, s3, v118
	v_add_u32_e32 v236, s69, v121
	v_xor_b32_e32 v242, 16, v144
	v_add_u32_e32 v232, s69, v118
	v_add_u32_e32 v228, s67, v116
	v_add_u32_e32 v238, s69, v122
	v_add_u32_e32 v234, s67, v120
	v_add_u32_e32 v235, s3, v121
	v_add_u32_e32 v215, v92, v111
	v_add_u32_e32 v220, v91, v111
	v_add_u32_e32 v212, v91, v45
	v_xor_b32_e32 v243, 32, v144
	v_and_b32_e32 v241, 64, v144
	v_add_u32_e32 v21, 64, v241
	v_cmp_lt_i32_e32 vcc, v243, v21
	s_nop 1
	v_cndmask_b32_e32 v20, v144, v243, vcc
	v_lshlrev_b32_e32 v222, 2, v20
	v_add_u32_e32 v227, s67, v115
	v_add_u32_e32 v230, s69, v117
	v_add_u32_e32 v213, s67, v109
	v_add_u32_e32 v209, v95, v108
	v_add_u32_e32 v237, s3, v122
	v_add_u32_e32 v217, v95, v112
	v_add_u32_e32 v226, s83, v102
	v_add_u32_e32 v208, v94, v108
	v_add_u32_e32 v210, v96, v108
	v_or_b32_e32 v240, v102, v241
	v_add_u32_e32 v219, v93, v111
	v_add_u32_e32 v233, s67, v119
	v_add_u32_e32 v225, 0x15d80, v44
	v_add_u32_e32 v218, v96, v112
	v_add_u32_e32 v216, v94, v112
	v_add_u32_e32 v224, s71, v114
	v_add_u32_e32 v211, v93, v45
	v_add_u32_e32 v229, s3, v117
	v_cmp_lt_i32_e32 vcc, v242, v21
	s_nop 1
	v_cndmask_b32_e32 v22, v144, v242, vcc
	v_lshlrev_b32_e32 v221, 2, v22
	v_add_u32_e32 v223, s67, v113
	v_add_u32_e32 v214, s71, v110
	v_add_u32_e32 v239, 0x12600, v97
	v_add_u32_e32 v207, v92, v45
	s_waitcnt vmcnt(0)

.LBB0_1332:
	v_lshl_add_u32 v132, s18, 8, v146
	s_lshl_b32 s24, s34, 9
	s_or_b32 s24, s24, s57
	v_or_b32_e32 v133, s24, v145
	s_lshl_b32 s24, s34, 2
	s_or_b32 s26, s24, s52
	v_cmp_gt_i32_e64 s[0:1], s67, v132
	v_lshl_or_b32 v162, v132, 11, v133
	v_mov_b32_e32 v170, 0
	v_cndmask_b32_e64 v250, 0, v132, s[0:1]
	v_ashrrev_i32_e32 v251, 31, v250
	v_lshl_add_u64 v[250:251], v[250:251], 2, s[10:11]
	global_load_dword v154, v[250:251], off
	s_and_saveexec_b64 s[24:25], s[0:1]
	global_load_dwordx4 v[178:181], v162, s[6:7]
	global_load_dwordx4 v[182:185], v162, s[6:7] offset:256
	s_mov_b64 exec, s[24:25]
	v_or_b32_e32 v128, 16, v132
	v_cmp_gt_i32_e64 s[0:1], s67, v128
	v_lshl_or_b32 v163, v128, 11, v133
	v_mov_b32_e32 v171, 0
	v_cndmask_b32_e64 v250, 0, v128, s[0:1]
	v_ashrrev_i32_e32 v251, 31, v250
	v_lshl_add_u64 v[250:251], v[250:251], 2, s[10:11]
	global_load_dword v155, v[250:251], off
	s_and_saveexec_b64 s[24:25], s[0:1]
	global_load_dwordx4 v[186:189], v163, s[6:7]
	global_load_dwordx4 v[190:193], v163, s[6:7] offset:256
	s_mov_b64 exec, s[24:25]
	v_or_b32_e32 v128, 32, v132
	v_cmp_gt_i32_e64 s[0:1], s67, v128
	v_lshl_or_b32 v164, v128, 11, v133
	v_mov_b32_e32 v172, 0
	v_cndmask_b32_e64 v250, 0, v128, s[0:1]
	v_ashrrev_i32_e32 v251, 31, v250
	v_lshl_add_u64 v[250:251], v[250:251], 2, s[10:11]
	global_load_dword v156, v[250:251], off
	s_and_saveexec_b64 s[24:25], s[0:1]
	global_load_dwordx4 v[194:197], v164, s[6:7]
	global_load_dwordx4 v[198:201], v164, s[6:7] offset:256
	s_mov_b64 exec, s[24:25]
	v_or_b32_e32 v128, 48, v132
	v_cmp_gt_i32_e64 s[0:1], s67, v128
	v_lshl_or_b32 v165, v128, 11, v133
	v_mov_b32_e32 v173, 0
	v_cndmask_b32_e64 v250, 0, v128, s[0:1]
	v_ashrrev_i32_e32 v251, 31, v250
	v_lshl_add_u64 v[250:251], v[250:251], 2, s[10:11]
	global_load_dword v157, v[250:251], off
	s_and_saveexec_b64 s[24:25], s[0:1]
	global_load_dwordx4 v[202:205], v165, s[6:7]
	global_load_dwordx4 v[206:209], v165, s[6:7] offset:256
	s_mov_b64 exec, s[24:25]
	v_add_u32_e32 v128, 0x80, v132
	v_cmp_gt_i32_e64 s[0:1], s67, v128
	v_lshl_or_b32 v166, v128, 11, v133
	v_mov_b32_e32 v174, 0
	v_cndmask_b32_e64 v250, 0, v128, s[0:1]
	v_ashrrev_i32_e32 v251, 31, v250
	v_lshl_add_u64 v[250:251], v[250:251], 2, s[10:11]
	global_load_dword v158, v[250:251], off
	s_and_saveexec_b64 s[24:25], s[0:1]
	global_load_dwordx4 v[210:213], v166, s[6:7]
	global_load_dwordx4 v[214:217], v166, s[6:7] offset:256
	s_mov_b64 exec, s[24:25]
	v_add_u32_e32 v128, 0x90, v132
	v_cmp_gt_i32_e64 s[0:1], s67, v128
	v_lshl_or_b32 v167, v128, 11, v133
	v_mov_b32_e32 v175, 0
	v_cndmask_b32_e64 v250, 0, v128, s[0:1]
	v_ashrrev_i32_e32 v251, 31, v250
	v_lshl_add_u64 v[250:251], v[250:251], 2, s[10:11]
	global_load_dword v159, v[250:251], off
	s_and_saveexec_b64 s[24:25], s[0:1]
	global_load_dwordx4 v[218:221], v167, s[6:7]
	global_load_dwordx4 v[222:225], v167, s[6:7] offset:256
	s_mov_b64 exec, s[24:25]
	v_add_u32_e32 v128, 0xa0, v132
	v_cmp_gt_i32_e64 s[0:1], s67, v128
	v_lshl_or_b32 v168, v128, 11, v133
	v_mov_b32_e32 v176, 0
	v_cndmask_b32_e64 v250, 0, v128, s[0:1]
	v_ashrrev_i32_e32 v251, 31, v250
	v_lshl_add_u64 v[250:251], v[250:251], 2, s[10:11]
	global_load_dword v160, v[250:251], off
	s_and_saveexec_b64 s[24:25], s[0:1]
	global_load_dwordx4 v[226:229], v168, s[6:7]
	global_load_dwordx4 v[230:233], v168, s[6:7] offset:256
	s_mov_b64 exec, s[24:25]
	v_add_u32_e32 v128, 0xb0, v132
	v_cmp_gt_i32_e64 s[0:1], s67, v128
	v_lshl_or_b32 v169, v128, 11, v133
	v_mov_b32_e32 v177, 0
	v_cndmask_b32_e64 v250, 0, v128, s[0:1]
	v_ashrrev_i32_e32 v251, 31, v250
	v_lshl_add_u64 v[250:251], v[250:251], 2, s[10:11]
	global_load_dword v161, v[250:251], off
	s_and_saveexec_b64 s[24:25], s[0:1]
	global_load_dwordx4 v[234:237], v169, s[6:7]
	global_load_dwordx4 v[238:241], v169, s[6:7] offset:256
	s_mov_b64 exec, s[24:25]
	v_and_b32_e32 v137, 64, v142
	v_xor_b32_e32 v136, 16, v142
	v_add_u32_e32 v137, 64, v137
	v_xor_b32_e32 v138, 32, v142
	v_cmp_lt_i32_e32 vcc, v136, v137
	s_nop 1
	v_cndmask_b32_e32 v136, v142, v136, vcc
	v_lshlrev_b32_e32 v134, 2, v136
	v_cmp_lt_i32_e32 vcc, v138, v137
	s_nop 1
	v_cndmask_b32_e32 v137, v142, v138, vcc
	v_lshlrev_b32_e32 v135, 2, v137
	v_cmp_eq_u32_e32 vcc, 0, v144
	v_cmp_gt_i32_e64 s[0:1], s67, v132
	s_waitcnt vmcnt(23)
	v_mov_b32_e32 v130, v154
	v_mov_b32_e32 v131, v154
	s_and_saveexec_b64 s[24:25], s[0:1]
	s_waitcnt vmcnt(22)
	v_cvt_f32_f16_e32 v146, v178
	v_cvt_f32_f16_sdwa v147, v178 dst_sel:DWORD dst_unused:UNUSED_PAD src0_sel:WORD_1
	v_cvt_f32_f16_e32 v148, v179
	v_cvt_f32_f16_sdwa v149, v179 dst_sel:DWORD dst_unused:UNUSED_PAD src0_sel:WORD_1
	v_cvt_f32_f16_e32 v150, v180
	v_cvt_f32_f16_sdwa v151, v180 dst_sel:DWORD dst_unused:UNUSED_PAD src0_sel:WORD_1
	v_cvt_f32_f16_e32 v152, v181
	v_cvt_f32_f16_sdwa v153, v181 dst_sel:DWORD dst_unused:UNUSED_PAD src0_sel:WORD_1
	v_pk_fma_f32 v[124:125], v[130:131], v[146:147], v[124:125]
	v_pk_fma_f32 v[126:127], v[130:131], v[148:149], v[126:127]
	v_pk_fma_f32 v[120:121], v[130:131], v[150:151], v[120:121]
	v_pk_fma_f32 v[122:123], v[130:131], v[152:153], v[122:123]
	v_cvt_pk_f16_f32 v178, v124, v125
	v_cvt_pk_f16_f32 v179, v126, v127
	v_cvt_pk_f16_f32 v180, v120, v121
	v_cvt_pk_f16_f32 v181, v122, v123
	v_pk_mul_f32 v[124:125], v[124:125], v[124:125]
	v_pk_mul_f32 v[126:127], v[126:127], v[126:127]
	v_pk_mul_f32 v[120:121], v[120:121], v[120:121]
	v_pk_mul_f32 v[122:123], v[122:123], v[122:123]
	global_store_dwordx4 v162, v[178:181], s[8:9] sc1
	s_nop 1
	v_add_f32_e32 v136, v124, v125
	v_add_f32_e32 v137, v126, v127
	v_add_f32_e32 v138, v120, v121
	v_add_f32_e32 v139, v122, v123
	v_add_f32_e32 v136, v136, v137
	v_add_f32_e32 v136, v138, v136
	v_add_f32_e32 v170, v139, v136
	s_waitcnt vmcnt(22)
	v_cvt_f32_f16_e32 v146, v182
	v_cvt_f32_f16_sdwa v147, v182 dst_sel:DWORD dst_unused:UNUSED_PAD src0_sel:WORD_1
	v_cvt_f32_f16_e32 v148, v183
	v_cvt_f32_f16_sdwa v149, v183 dst_sel:DWORD dst_unused:UNUSED_PAD src0_sel:WORD_1
	v_cvt_f32_f16_e32 v150, v184
	v_cvt_f32_f16_sdwa v151, v184 dst_sel:DWORD dst_unused:UNUSED_PAD src0_sel:WORD_1
	v_cvt_f32_f16_e32 v152, v185
	v_cvt_f32_f16_sdwa v153, v185 dst_sel:DWORD dst_unused:UNUSED_PAD src0_sel:WORD_1
	v_pk_fma_f32 v[116:117], v[130:131], v[146:147], v[116:117]
	v_pk_fma_f32 v[118:119], v[130:131], v[148:149], v[118:119]
	v_pk_fma_f32 v[112:113], v[130:131], v[150:151], v[112:113]
	v_pk_fma_f32 v[114:115], v[130:131], v[152:153], v[114:115]
	v_cvt_pk_f16_f32 v182, v116, v117
	v_cvt_pk_f16_f32 v183, v118, v119
	v_cvt_pk_f16_f32 v184, v112, v113
	v_cvt_pk_f16_f32 v185, v114, v115
	v_pk_mul_f32 v[116:117], v[116:117], v[116:117]
	v_pk_mul_f32 v[118:119], v[118:119], v[118:119]
	v_pk_mul_f32 v[112:113], v[112:113], v[112:113]
	v_pk_mul_f32 v[114:115], v[114:115], v[114:115]
	global_store_dwordx4 v162, v[182:185], s[8:9] offset:256 sc1
	s_nop 1
	v_add_f32_e32 v136, v116, v117
	v_add_f32_e32 v137, v118, v119
	v_add_f32_e32 v138, v112, v113
	v_add_f32_e32 v139, v114, v115
	v_add_f32_e32 v136, v136, v137
	v_add_f32_e32 v136, v138, v136
	v_add_f32_e32 v136, v139, v136
	v_add_f32_e32 v170, v170, v136
	s_mov_b64 exec, s[24:25]
	v_or_b32_e32 v128, 16, v132
	v_cmp_gt_i32_e64 s[0:1], s67, v128
	s_waitcnt vmcnt(22)
	v_mov_b32_e32 v130, v155
	v_mov_b32_e32 v131, v155
	s_and_saveexec_b64 s[24:25], s[0:1]
	s_waitcnt vmcnt(21)
	v_cvt_f32_f16_e32 v146, v186
	v_cvt_f32_f16_sdwa v147, v186 dst_sel:DWORD dst_unused:UNUSED_PAD src0_sel:WORD_1
	v_cvt_f32_f16_e32 v148, v187
	v_cvt_f32_f16_sdwa v149, v187 dst_sel:DWORD dst_unused:UNUSED_PAD src0_sel:WORD_1
	v_cvt_f32_f16_e32 v150, v188
	v_cvt_f32_f16_sdwa v151, v188 dst_sel:DWORD dst_unused:UNUSED_PAD src0_sel:WORD_1
	v_cvt_f32_f16_e32 v152, v189
	v_cvt_f32_f16_sdwa v153, v189 dst_sel:DWORD dst_unused:UNUSED_PAD src0_sel:WORD_1
	v_pk_fma_f32 v[108:109], v[130:131], v[146:147], v[108:109]
	v_pk_fma_f32 v[110:111], v[130:131], v[148:149], v[110:111]
	v_pk_fma_f32 v[104:105], v[130:131], v[150:151], v[104:105]
	v_pk_fma_f32 v[106:107], v[130:131], v[152:153], v[106:107]
	v_cvt_pk_f16_f32 v186, v108, v109
	v_cvt_pk_f16_f32 v187, v110, v111
	v_cvt_pk_f16_f32 v188, v104, v105
	v_cvt_pk_f16_f32 v189, v106, v107
	v_pk_mul_f32 v[108:109], v[108:109], v[108:109]
	v_pk_mul_f32 v[110:111], v[110:111], v[110:111]
	v_pk_mul_f32 v[104:105], v[104:105], v[104:105]
	v_pk_mul_f32 v[106:107], v[106:107], v[106:107]
	global_store_dwordx4 v163, v[186:189], s[8:9] sc1
	s_nop 1
	v_add_f32_e32 v136, v108, v109
	v_add_f32_e32 v137, v110, v111
	v_add_f32_e32 v138, v104, v105
	v_add_f32_e32 v139, v106, v107
	v_add_f32_e32 v136, v136, v137
	v_add_f32_e32 v136, v138, v136
	v_add_f32_e32 v171, v139, v136
	s_waitcnt vmcnt(21)
	v_cvt_f32_f16_e32 v146, v190
	v_cvt_f32_f16_sdwa v147, v190 dst_sel:DWORD dst_unused:UNUSED_PAD src0_sel:WORD_1
	v_cvt_f32_f16_e32 v148, v191
	v_cvt_f32_f16_sdwa v149, v191 dst_sel:DWORD dst_unused:UNUSED_PAD src0_sel:WORD_1
	v_cvt_f32_f16_e32 v150, v192
	v_cvt_f32_f16_sdwa v151, v192 dst_sel:DWORD dst_unused:UNUSED_PAD src0_sel:WORD_1
	v_cvt_f32_f16_e32 v152, v193
	v_cvt_f32_f16_sdwa v153, v193 dst_sel:DWORD dst_unused:UNUSED_PAD src0_sel:WORD_1
	v_pk_fma_f32 v[100:101], v[130:131], v[146:147], v[100:101]
	v_pk_fma_f32 v[102:103], v[130:131], v[148:149], v[102:103]
	v_pk_fma_f32 v[96:97], v[130:131], v[150:151], v[96:97]
	v_pk_fma_f32 v[98:99], v[130:131], v[152:153], v[98:99]
	v_cvt_pk_f16_f32 v190, v100, v101
	v_cvt_pk_f16_f32 v191, v102, v103
	v_cvt_pk_f16_f32 v192, v96, v97
	v_cvt_pk_f16_f32 v193, v98, v99
	v_pk_mul_f32 v[100:101], v[100:101], v[100:101]
	v_pk_mul_f32 v[102:103], v[102:103], v[102:103]
	v_pk_mul_f32 v[96:97], v[96:97], v[96:97]
	v_pk_mul_f32 v[98:99], v[98:99], v[98:99]
	global_store_dwordx4 v163, v[190:193], s[8:9] offset:256 sc1
	s_nop 1
	v_add_f32_e32 v136, v100, v101
	v_add_f32_e32 v137, v102, v103
	v_add_f32_e32 v138, v96, v97
	v_add_f32_e32 v139, v98, v99
	v_add_f32_e32 v136, v136, v137
	v_add_f32_e32 v136, v138, v136
	v_add_f32_e32 v136, v139, v136
	v_add_f32_e32 v171, v171, v136
	s_mov_b64 exec, s[24:25]
	v_or_b32_e32 v128, 32, v132
	v_cmp_gt_i32_e64 s[0:1], s67, v128
	s_waitcnt vmcnt(21)
	v_mov_b32_e32 v130, v156
	v_mov_b32_e32 v131, v156
	s_and_saveexec_b64 s[24:25], s[0:1]
	s_waitcnt vmcnt(20)
	v_cvt_f32_f16_e32 v146, v194
	v_cvt_f32_f16_sdwa v147, v194 dst_sel:DWORD dst_unused:UNUSED_PAD src0_sel:WORD_1
	v_cvt_f32_f16_e32 v148, v195
	v_cvt_f32_f16_sdwa v149, v195 dst_sel:DWORD dst_unused:UNUSED_PAD src0_sel:WORD_1
	v_cvt_f32_f16_e32 v150, v196
	v_cvt_f32_f16_sdwa v151, v196 dst_sel:DWORD dst_unused:UNUSED_PAD src0_sel:WORD_1
	v_cvt_f32_f16_e32 v152, v197
	v_cvt_f32_f16_sdwa v153, v197 dst_sel:DWORD dst_unused:UNUSED_PAD src0_sel:WORD_1
	v_pk_fma_f32 v[92:93], v[130:131], v[146:147], v[92:93]
	v_pk_fma_f32 v[94:95], v[130:131], v[148:149], v[94:95]
	v_pk_fma_f32 v[88:89], v[130:131], v[150:151], v[88:89]
	v_pk_fma_f32 v[90:91], v[130:131], v[152:153], v[90:91]
	v_cvt_pk_f16_f32 v194, v92, v93
	v_cvt_pk_f16_f32 v195, v94, v95
	v_cvt_pk_f16_f32 v196, v88, v89
	v_cvt_pk_f16_f32 v197, v90, v91
	v_pk_mul_f32 v[92:93], v[92:93], v[92:93]
	v_pk_mul_f32 v[94:95], v[94:95], v[94:95]
	v_pk_mul_f32 v[88:89], v[88:89], v[88:89]
	v_pk_mul_f32 v[90:91], v[90:91], v[90:91]
	global_store_dwordx4 v164, v[194:197], s[8:9] sc1
	s_nop 1
	v_add_f32_e32 v136, v92, v93
	v_add_f32_e32 v137, v94, v95
	v_add_f32_e32 v138, v88, v89
	v_add_f32_e32 v139, v90, v91
	v_add_f32_e32 v136, v136, v137
	v_add_f32_e32 v136, v138, v136
	v_add_f32_e32 v172, v139, v136
	s_waitcnt vmcnt(20)
	v_cvt_f32_f16_e32 v146, v198
	v_cvt_f32_f16_sdwa v147, v198 dst_sel:DWORD dst_unused:UNUSED_PAD src0_sel:WORD_1
	v_cvt_f32_f16_e32 v148, v199
	v_cvt_f32_f16_sdwa v149, v199 dst_sel:DWORD dst_unused:UNUSED_PAD src0_sel:WORD_1
	v_cvt_f32_f16_e32 v150, v200
	v_cvt_f32_f16_sdwa v151, v200 dst_sel:DWORD dst_unused:UNUSED_PAD src0_sel:WORD_1
	v_cvt_f32_f16_e32 v152, v201
	v_cvt_f32_f16_sdwa v153, v201 dst_sel:DWORD dst_unused:UNUSED_PAD src0_sel:WORD_1
	v_pk_fma_f32 v[84:85], v[130:131], v[146:147], v[84:85]
	v_pk_fma_f32 v[86:87], v[130:131], v[148:149], v[86:87]
	v_pk_fma_f32 v[80:81], v[130:131], v[150:151], v[80:81]
	v_pk_fma_f32 v[82:83], v[130:131], v[152:153], v[82:83]
	v_cvt_pk_f16_f32 v198, v84, v85
	v_cvt_pk_f16_f32 v199, v86, v87
	v_cvt_pk_f16_f32 v200, v80, v81
	v_cvt_pk_f16_f32 v201, v82, v83
	v_pk_mul_f32 v[84:85], v[84:85], v[84:85]
	v_pk_mul_f32 v[86:87], v[86:87], v[86:87]
	v_pk_mul_f32 v[80:81], v[80:81], v[80:81]
	v_pk_mul_f32 v[82:83], v[82:83], v[82:83]
	global_store_dwordx4 v164, v[198:201], s[8:9] offset:256 sc1
	s_nop 1
	v_add_f32_e32 v136, v84, v85
	v_add_f32_e32 v137, v86, v87
	v_add_f32_e32 v138, v80, v81
	v_add_f32_e32 v139, v82, v83
	v_add_f32_e32 v136, v136, v137
	v_add_f32_e32 v136, v138, v136
	v_add_f32_e32 v136, v139, v136
	v_add_f32_e32 v172, v172, v136
	s_mov_b64 exec, s[24:25]
	v_or_b32_e32 v128, 48, v132
	v_cmp_gt_i32_e64 s[0:1], s67, v128
	s_waitcnt vmcnt(20)
	v_mov_b32_e32 v130, v157
	v_mov_b32_e32 v131, v157
	s_and_saveexec_b64 s[24:25], s[0:1]
	s_waitcnt vmcnt(19)
	v_cvt_f32_f16_e32 v146, v202
	v_cvt_f32_f16_sdwa v147, v202 dst_sel:DWORD dst_unused:UNUSED_PAD src0_sel:WORD_1
	v_cvt_f32_f16_e32 v148, v203
	v_cvt_f32_f16_sdwa v149, v203 dst_sel:DWORD dst_unused:UNUSED_PAD src0_sel:WORD_1
	v_cvt_f32_f16_e32 v150, v204
	v_cvt_f32_f16_sdwa v151, v204 dst_sel:DWORD dst_unused:UNUSED_PAD src0_sel:WORD_1
	v_cvt_f32_f16_e32 v152, v205
	v_cvt_f32_f16_sdwa v153, v205 dst_sel:DWORD dst_unused:UNUSED_PAD src0_sel:WORD_1
	v_pk_fma_f32 v[76:77], v[130:131], v[146:147], v[76:77]
	v_pk_fma_f32 v[78:79], v[130:131], v[148:149], v[78:79]
	v_pk_fma_f32 v[72:73], v[130:131], v[150:151], v[72:73]
	v_pk_fma_f32 v[74:75], v[130:131], v[152:153], v[74:75]
	v_cvt_pk_f16_f32 v202, v76, v77
	v_cvt_pk_f16_f32 v203, v78, v79
	v_cvt_pk_f16_f32 v204, v72, v73
	v_cvt_pk_f16_f32 v205, v74, v75
	v_pk_mul_f32 v[76:77], v[76:77], v[76:77]
	v_pk_mul_f32 v[78:79], v[78:79], v[78:79]
	v_pk_mul_f32 v[72:73], v[72:73], v[72:73]
	v_pk_mul_f32 v[74:75], v[74:75], v[74:75]
	global_store_dwordx4 v165, v[202:205], s[8:9] sc1
	s_nop 1
	v_add_f32_e32 v136, v76, v77
	v_add_f32_e32 v137, v78, v79
	v_add_f32_e32 v138, v72, v73
	v_add_f32_e32 v139, v74, v75
	v_add_f32_e32 v136, v136, v137
	v_add_f32_e32 v136, v138, v136
	v_add_f32_e32 v173, v139, v136
	s_waitcnt vmcnt(19)
	v_cvt_f32_f16_e32 v146, v206
	v_cvt_f32_f16_sdwa v147, v206 dst_sel:DWORD dst_unused:UNUSED_PAD src0_sel:WORD_1
	v_cvt_f32_f16_e32 v148, v207
	v_cvt_f32_f16_sdwa v149, v207 dst_sel:DWORD dst_unused:UNUSED_PAD src0_sel:WORD_1
	v_cvt_f32_f16_e32 v150, v208
	v_cvt_f32_f16_sdwa v151, v208 dst_sel:DWORD dst_unused:UNUSED_PAD src0_sel:WORD_1
	v_cvt_f32_f16_e32 v152, v209
	v_cvt_f32_f16_sdwa v153, v209 dst_sel:DWORD dst_unused:UNUSED_PAD src0_sel:WORD_1
	v_pk_fma_f32 v[68:69], v[130:131], v[146:147], v[68:69]
	v_pk_fma_f32 v[70:71], v[130:131], v[148:149], v[70:71]
	v_pk_fma_f32 v[64:65], v[130:131], v[150:151], v[64:65]
	v_pk_fma_f32 v[66:67], v[130:131], v[152:153], v[66:67]
	v_cvt_pk_f16_f32 v206, v68, v69
	v_cvt_pk_f16_f32 v207, v70, v71
	v_cvt_pk_f16_f32 v208, v64, v65
	v_cvt_pk_f16_f32 v209, v66, v67
	v_pk_mul_f32 v[68:69], v[68:69], v[68:69]
	v_pk_mul_f32 v[70:71], v[70:71], v[70:71]
	v_pk_mul_f32 v[64:65], v[64:65], v[64:65]
	v_pk_mul_f32 v[66:67], v[66:67], v[66:67]
	global_store_dwordx4 v165, v[206:209], s[8:9] offset:256 sc1
	s_nop 1
	v_add_f32_e32 v136, v68, v69
	v_add_f32_e32 v137, v70, v71
	v_add_f32_e32 v138, v64, v65
	v_add_f32_e32 v139, v66, v67
	v_add_f32_e32 v136, v136, v137
	v_add_f32_e32 v136, v138, v136
	v_add_f32_e32 v136, v139, v136
	v_add_f32_e32 v173, v173, v136
	s_mov_b64 exec, s[24:25]
	v_add_u32_e32 v128, 0x80, v132
	v_cmp_gt_i32_e64 s[0:1], s67, v128
	s_waitcnt vmcnt(19)
	v_mov_b32_e32 v130, v158
	v_mov_b32_e32 v131, v158
	s_and_saveexec_b64 s[24:25], s[0:1]
	s_waitcnt vmcnt(18)
	v_cvt_f32_f16_e32 v146, v210
	v_cvt_f32_f16_sdwa v147, v210 dst_sel:DWORD dst_unused:UNUSED_PAD src0_sel:WORD_1
	v_cvt_f32_f16_e32 v148, v211
	v_cvt_f32_f16_sdwa v149, v211 dst_sel:DWORD dst_unused:UNUSED_PAD src0_sel:WORD_1
	v_cvt_f32_f16_e32 v150, v212
	v_cvt_f32_f16_sdwa v151, v212 dst_sel:DWORD dst_unused:UNUSED_PAD src0_sel:WORD_1
	v_cvt_f32_f16_e32 v152, v213
	v_cvt_f32_f16_sdwa v153, v213 dst_sel:DWORD dst_unused:UNUSED_PAD src0_sel:WORD_1
	v_pk_fma_f32 v[60:61], v[130:131], v[146:147], v[60:61]
	v_pk_fma_f32 v[62:63], v[130:131], v[148:149], v[62:63]
	v_pk_fma_f32 v[56:57], v[130:131], v[150:151], v[56:57]
	v_pk_fma_f32 v[58:59], v[130:131], v[152:153], v[58:59]
	v_cvt_pk_f16_f32 v210, v60, v61
	v_cvt_pk_f16_f32 v211, v62, v63
	v_cvt_pk_f16_f32 v212, v56, v57
	v_cvt_pk_f16_f32 v213, v58, v59
	v_pk_mul_f32 v[60:61], v[60:61], v[60:61]
	v_pk_mul_f32 v[62:63], v[62:63], v[62:63]
	v_pk_mul_f32 v[56:57], v[56:57], v[56:57]
	v_pk_mul_f32 v[58:59], v[58:59], v[58:59]
	global_store_dwordx4 v166, v[210:213], s[8:9] sc1
	s_nop 1
	v_add_f32_e32 v136, v60, v61
	v_add_f32_e32 v137, v62, v63
	v_add_f32_e32 v138, v56, v57
	v_add_f32_e32 v139, v58, v59
	v_add_f32_e32 v136, v136, v137
	v_add_f32_e32 v136, v138, v136
	v_add_f32_e32 v174, v139, v136
	s_waitcnt vmcnt(18)
	v_cvt_f32_f16_e32 v146, v214
	v_cvt_f32_f16_sdwa v147, v214 dst_sel:DWORD dst_unused:UNUSED_PAD src0_sel:WORD_1
	v_cvt_f32_f16_e32 v148, v215
	v_cvt_f32_f16_sdwa v149, v215 dst_sel:DWORD dst_unused:UNUSED_PAD src0_sel:WORD_1
	v_cvt_f32_f16_e32 v150, v216
	v_cvt_f32_f16_sdwa v151, v216 dst_sel:DWORD dst_unused:UNUSED_PAD src0_sel:WORD_1
	v_cvt_f32_f16_e32 v152, v217
	v_cvt_f32_f16_sdwa v153, v217 dst_sel:DWORD dst_unused:UNUSED_PAD src0_sel:WORD_1
	v_pk_fma_f32 v[52:53], v[130:131], v[146:147], v[52:53]
	v_pk_fma_f32 v[54:55], v[130:131], v[148:149], v[54:55]
	v_pk_fma_f32 v[48:49], v[130:131], v[150:151], v[48:49]
	v_pk_fma_f32 v[50:51], v[130:131], v[152:153], v[50:51]
	v_cvt_pk_f16_f32 v214, v52, v53
	v_cvt_pk_f16_f32 v215, v54, v55
	v_cvt_pk_f16_f32 v216, v48, v49
	v_cvt_pk_f16_f32 v217, v50, v51
	v_pk_mul_f32 v[52:53], v[52:53], v[52:53]
	v_pk_mul_f32 v[54:55], v[54:55], v[54:55]
	v_pk_mul_f32 v[48:49], v[48:49], v[48:49]
	v_pk_mul_f32 v[50:51], v[50:51], v[50:51]
	global_store_dwordx4 v166, v[214:217], s[8:9] offset:256 sc1
	s_nop 1
	v_add_f32_e32 v136, v52, v53
	v_add_f32_e32 v137, v54, v55
	v_add_f32_e32 v138, v48, v49
	v_add_f32_e32 v139, v50, v51
	v_add_f32_e32 v136, v136, v137
	v_add_f32_e32 v136, v138, v136
	v_add_f32_e32 v136, v139, v136
	v_add_f32_e32 v174, v174, v136
	s_mov_b64 exec, s[24:25]
	v_add_u32_e32 v128, 0x90, v132
	v_cmp_gt_i32_e64 s[0:1], s67, v128
	s_waitcnt vmcnt(18)
	v_mov_b32_e32 v130, v159
	v_mov_b32_e32 v131, v159
	s_and_saveexec_b64 s[24:25], s[0:1]
	s_waitcnt vmcnt(17)
	v_cvt_f32_f16_e32 v146, v218
	v_cvt_f32_f16_sdwa v147, v218 dst_sel:DWORD dst_unused:UNUSED_PAD src0_sel:WORD_1
	v_cvt_f32_f16_e32 v148, v219
	v_cvt_f32_f16_sdwa v149, v219 dst_sel:DWORD dst_unused:UNUSED_PAD src0_sel:WORD_1
	v_cvt_f32_f16_e32 v150, v220
	v_cvt_f32_f16_sdwa v151, v220 dst_sel:DWORD dst_unused:UNUSED_PAD src0_sel:WORD_1
	v_cvt_f32_f16_e32 v152, v221
	v_cvt_f32_f16_sdwa v153, v221 dst_sel:DWORD dst_unused:UNUSED_PAD src0_sel:WORD_1
	v_pk_fma_f32 v[44:45], v[130:131], v[146:147], v[44:45]
	v_pk_fma_f32 v[46:47], v[130:131], v[148:149], v[46:47]
	v_pk_fma_f32 v[40:41], v[130:131], v[150:151], v[40:41]
	v_pk_fma_f32 v[42:43], v[130:131], v[152:153], v[42:43]
	v_cvt_pk_f16_f32 v218, v44, v45
	v_cvt_pk_f16_f32 v219, v46, v47
	v_cvt_pk_f16_f32 v220, v40, v41
	v_cvt_pk_f16_f32 v221, v42, v43
	v_pk_mul_f32 v[44:45], v[44:45], v[44:45]
	v_pk_mul_f32 v[46:47], v[46:47], v[46:47]
	v_pk_mul_f32 v[40:41], v[40:41], v[40:41]
	v_pk_mul_f32 v[42:43], v[42:43], v[42:43]
	global_store_dwordx4 v167, v[218:221], s[8:9] sc1
	s_nop 1
	v_add_f32_e32 v136, v44, v45
	v_add_f32_e32 v137, v46, v47
	v_add_f32_e32 v138, v40, v41
	v_add_f32_e32 v139, v42, v43
	v_add_f32_e32 v136, v136, v137
	v_add_f32_e32 v136, v138, v136
	v_add_f32_e32 v175, v139, v136
	s_waitcnt vmcnt(17)
	v_cvt_f32_f16_e32 v146, v222
	v_cvt_f32_f16_sdwa v147, v222 dst_sel:DWORD dst_unused:UNUSED_PAD src0_sel:WORD_1
	v_cvt_f32_f16_e32 v148, v223
	v_cvt_f32_f16_sdwa v149, v223 dst_sel:DWORD dst_unused:UNUSED_PAD src0_sel:WORD_1
	v_cvt_f32_f16_e32 v150, v224
	v_cvt_f32_f16_sdwa v151, v224 dst_sel:DWORD dst_unused:UNUSED_PAD src0_sel:WORD_1
	v_cvt_f32_f16_e32 v152, v225
	v_cvt_f32_f16_sdwa v153, v225 dst_sel:DWORD dst_unused:UNUSED_PAD src0_sel:WORD_1
	v_pk_fma_f32 v[36:37], v[130:131], v[146:147], v[36:37]
	v_pk_fma_f32 v[38:39], v[130:131], v[148:149], v[38:39]
	v_pk_fma_f32 v[32:33], v[130:131], v[150:151], v[32:33]
	v_pk_fma_f32 v[34:35], v[130:131], v[152:153], v[34:35]
	v_cvt_pk_f16_f32 v222, v36, v37
	v_cvt_pk_f16_f32 v223, v38, v39
	v_cvt_pk_f16_f32 v224, v32, v33
	v_cvt_pk_f16_f32 v225, v34, v35
	v_pk_mul_f32 v[36:37], v[36:37], v[36:37]
	v_pk_mul_f32 v[38:39], v[38:39], v[38:39]
	v_pk_mul_f32 v[32:33], v[32:33], v[32:33]
	v_pk_mul_f32 v[34:35], v[34:35], v[34:35]
	global_store_dwordx4 v167, v[222:225], s[8:9] offset:256 sc1
	s_nop 1
	v_add_f32_e32 v136, v36, v37
	v_add_f32_e32 v137, v38, v39
	v_add_f32_e32 v138, v32, v33
	v_add_f32_e32 v139, v34, v35
	v_add_f32_e32 v136, v136, v137
	v_add_f32_e32 v136, v138, v136
	v_add_f32_e32 v136, v139, v136
	v_add_f32_e32 v175, v175, v136
	s_mov_b64 exec, s[24:25]
	v_add_u32_e32 v128, 0xa0, v132
	v_cmp_gt_i32_e64 s[0:1], s67, v128
	s_waitcnt vmcnt(17)
	v_mov_b32_e32 v130, v160
	v_mov_b32_e32 v131, v160
	s_and_saveexec_b64 s[24:25], s[0:1]
	s_waitcnt vmcnt(16)
	v_cvt_f32_f16_e32 v146, v226
	v_cvt_f32_f16_sdwa v147, v226 dst_sel:DWORD dst_unused:UNUSED_PAD src0_sel:WORD_1
	v_cvt_f32_f16_e32 v148, v227
	v_cvt_f32_f16_sdwa v149, v227 dst_sel:DWORD dst_unused:UNUSED_PAD src0_sel:WORD_1
	v_cvt_f32_f16_e32 v150, v228
	v_cvt_f32_f16_sdwa v151, v228 dst_sel:DWORD dst_unused:UNUSED_PAD src0_sel:WORD_1
	v_cvt_f32_f16_e32 v152, v229
	v_cvt_f32_f16_sdwa v153, v229 dst_sel:DWORD dst_unused:UNUSED_PAD src0_sel:WORD_1
	v_pk_fma_f32 v[28:29], v[130:131], v[146:147], v[28:29]
	v_pk_fma_f32 v[30:31], v[130:131], v[148:149], v[30:31]
	v_pk_fma_f32 v[24:25], v[130:131], v[150:151], v[24:25]
	v_pk_fma_f32 v[26:27], v[130:131], v[152:153], v[26:27]
	v_cvt_pk_f16_f32 v226, v28, v29
	v_cvt_pk_f16_f32 v227, v30, v31
	v_cvt_pk_f16_f32 v228, v24, v25
	v_cvt_pk_f16_f32 v229, v26, v27
	v_pk_mul_f32 v[28:29], v[28:29], v[28:29]
	v_pk_mul_f32 v[30:31], v[30:31], v[30:31]
	v_pk_mul_f32 v[24:25], v[24:25], v[24:25]
	v_pk_mul_f32 v[26:27], v[26:27], v[26:27]
	global_store_dwordx4 v168, v[226:229], s[8:9] sc1
	s_nop 1
	v_add_f32_e32 v136, v28, v29
	v_add_f32_e32 v137, v30, v31
	v_add_f32_e32 v138, v24, v25
	v_add_f32_e32 v139, v26, v27
	v_add_f32_e32 v136, v136, v137
	v_add_f32_e32 v136, v138, v136
	v_add_f32_e32 v176, v139, v136
	s_waitcnt vmcnt(16)
	v_cvt_f32_f16_e32 v146, v230
	v_cvt_f32_f16_sdwa v147, v230 dst_sel:DWORD dst_unused:UNUSED_PAD src0_sel:WORD_1
	v_cvt_f32_f16_e32 v148, v231
	v_cvt_f32_f16_sdwa v149, v231 dst_sel:DWORD dst_unused:UNUSED_PAD src0_sel:WORD_1
	v_cvt_f32_f16_e32 v150, v232
	v_cvt_f32_f16_sdwa v151, v232 dst_sel:DWORD dst_unused:UNUSED_PAD src0_sel:WORD_1
	v_cvt_f32_f16_e32 v152, v233
	v_cvt_f32_f16_sdwa v153, v233 dst_sel:DWORD dst_unused:UNUSED_PAD src0_sel:WORD_1
	v_pk_fma_f32 v[20:21], v[130:131], v[146:147], v[20:21]
	v_pk_fma_f32 v[22:23], v[130:131], v[148:149], v[22:23]
	v_pk_fma_f32 v[16:17], v[130:131], v[150:151], v[16:17]
	v_pk_fma_f32 v[18:19], v[130:131], v[152:153], v[18:19]
	v_cvt_pk_f16_f32 v230, v20, v21
	v_cvt_pk_f16_f32 v231, v22, v23
	v_cvt_pk_f16_f32 v232, v16, v17
	v_cvt_pk_f16_f32 v233, v18, v19
	v_pk_mul_f32 v[20:21], v[20:21], v[20:21]
	v_pk_mul_f32 v[22:23], v[22:23], v[22:23]
	v_pk_mul_f32 v[16:17], v[16:17], v[16:17]
	v_pk_mul_f32 v[18:19], v[18:19], v[18:19]
	global_store_dwordx4 v168, v[230:233], s[8:9] offset:256 sc1
	s_nop 1
	v_add_f32_e32 v136, v20, v21
	v_add_f32_e32 v137, v22, v23
	v_add_f32_e32 v138, v16, v17
	v_add_f32_e32 v139, v18, v19
	v_add_f32_e32 v136, v136, v137
	v_add_f32_e32 v136, v138, v136
	v_add_f32_e32 v136, v139, v136
	v_add_f32_e32 v176, v176, v136
	s_mov_b64 exec, s[24:25]
	v_add_u32_e32 v128, 0xb0, v132
	v_cmp_gt_i32_e64 s[0:1], s67, v128
	s_waitcnt vmcnt(16)
	v_mov_b32_e32 v130, v161
	v_mov_b32_e32 v131, v161
	s_and_saveexec_b64 s[24:25], s[0:1]
	s_waitcnt vmcnt(15)
	v_cvt_f32_f16_e32 v146, v234
	v_cvt_f32_f16_sdwa v147, v234 dst_sel:DWORD dst_unused:UNUSED_PAD src0_sel:WORD_1
	v_cvt_f32_f16_e32 v148, v235
	v_cvt_f32_f16_sdwa v149, v235 dst_sel:DWORD dst_unused:UNUSED_PAD src0_sel:WORD_1
	v_cvt_f32_f16_e32 v150, v236
	v_cvt_f32_f16_sdwa v151, v236 dst_sel:DWORD dst_unused:UNUSED_PAD src0_sel:WORD_1
	v_cvt_f32_f16_e32 v152, v237
	v_cvt_f32_f16_sdwa v153, v237 dst_sel:DWORD dst_unused:UNUSED_PAD src0_sel:WORD_1
	v_pk_fma_f32 v[12:13], v[130:131], v[146:147], v[12:13]
	v_pk_fma_f32 v[14:15], v[130:131], v[148:149], v[14:15]
	v_pk_fma_f32 v[8:9], v[130:131], v[150:151], v[8:9]
	v_pk_fma_f32 v[10:11], v[130:131], v[152:153], v[10:11]
	v_cvt_pk_f16_f32 v234, v12, v13
	v_cvt_pk_f16_f32 v235, v14, v15
	v_cvt_pk_f16_f32 v236, v8, v9
	v_cvt_pk_f16_f32 v237, v10, v11
	v_pk_mul_f32 v[12:13], v[12:13], v[12:13]
	v_pk_mul_f32 v[14:15], v[14:15], v[14:15]
	v_pk_mul_f32 v[8:9], v[8:9], v[8:9]
	v_pk_mul_f32 v[10:11], v[10:11], v[10:11]
	global_store_dwordx4 v169, v[234:237], s[8:9] sc1
	s_nop 1
	v_add_f32_e32 v136, v12, v13
	v_add_f32_e32 v137, v14, v15
	v_add_f32_e32 v138, v8, v9
	v_add_f32_e32 v139, v10, v11
	v_add_f32_e32 v136, v136, v137
	v_add_f32_e32 v136, v138, v136
	v_add_f32_e32 v177, v139, v136
	s_waitcnt vmcnt(15)
	v_cvt_f32_f16_e32 v146, v238
	v_cvt_f32_f16_sdwa v147, v238 dst_sel:DWORD dst_unused:UNUSED_PAD src0_sel:WORD_1
	v_cvt_f32_f16_e32 v148, v239
	v_cvt_f32_f16_sdwa v149, v239 dst_sel:DWORD dst_unused:UNUSED_PAD src0_sel:WORD_1
	v_cvt_f32_f16_e32 v150, v240
	v_cvt_f32_f16_sdwa v151, v240 dst_sel:DWORD dst_unused:UNUSED_PAD src0_sel:WORD_1
	v_cvt_f32_f16_e32 v152, v241
	v_cvt_f32_f16_sdwa v153, v241 dst_sel:DWORD dst_unused:UNUSED_PAD src0_sel:WORD_1
	v_pk_fma_f32 v[4:5], v[130:131], v[146:147], v[4:5]
	v_pk_fma_f32 v[6:7], v[130:131], v[148:149], v[6:7]
	v_pk_fma_f32 v[0:1], v[130:131], v[150:151], v[0:1]
	v_pk_fma_f32 v[2:3], v[130:131], v[152:153], v[2:3]
	v_cvt_pk_f16_f32 v238, v4, v5
	v_cvt_pk_f16_f32 v239, v6, v7
	v_cvt_pk_f16_f32 v240, v0, v1
	v_cvt_pk_f16_f32 v241, v2, v3
	v_pk_mul_f32 v[4:5], v[4:5], v[4:5]
	v_pk_mul_f32 v[6:7], v[6:7], v[6:7]
	v_pk_mul_f32 v[0:1], v[0:1], v[0:1]
	v_pk_mul_f32 v[2:3], v[2:3], v[2:3]
	global_store_dwordx4 v169, v[238:241], s[8:9] offset:256 sc1
	s_nop 1
	v_add_f32_e32 v136, v4, v5
	v_add_f32_e32 v137, v6, v7
	v_add_f32_e32 v138, v0, v1
	v_add_f32_e32 v139, v2, v3
	v_add_f32_e32 v136, v136, v137
	v_add_f32_e32 v136, v138, v136
	v_add_f32_e32 v136, v139, v136
	v_add_f32_e32 v177, v177, v136
	s_mov_b64 exec, s[24:25]
	ds_bpermute_b32 v242, v134, v170
	ds_bpermute_b32 v243, v134, v171
	ds_bpermute_b32 v244, v134, v172
	ds_bpermute_b32 v245, v134, v173
	ds_bpermute_b32 v246, v134, v174
	ds_bpermute_b32 v247, v134, v175
	ds_bpermute_b32 v248, v134, v176
	ds_bpermute_b32 v249, v134, v177
	s_waitcnt lgkmcnt(7)
	v_add_f32_e32 v242, v170, v242
	s_waitcnt lgkmcnt(6)
	v_add_f32_e32 v243, v171, v243
	s_waitcnt lgkmcnt(5)
	v_add_f32_e32 v244, v172, v244
	s_waitcnt lgkmcnt(4)
	v_add_f32_e32 v245, v173, v245
	s_waitcnt lgkmcnt(3)
	v_add_f32_e32 v246, v174, v246
	s_waitcnt lgkmcnt(2)
	v_add_f32_e32 v247, v175, v247
	s_waitcnt lgkmcnt(1)
	v_add_f32_e32 v248, v176, v248
	s_waitcnt lgkmcnt(0)
	v_add_f32_e32 v249, v177, v249
	s_nop 0
	ds_bpermute_b32 v0, v135, v242
	ds_bpermute_b32 v1, v135, v243
	ds_bpermute_b32 v2, v135, v244
	ds_bpermute_b32 v3, v135, v245
	ds_bpermute_b32 v4, v135, v246
	ds_bpermute_b32 v5, v135, v247
	ds_bpermute_b32 v6, v135, v248
	ds_bpermute_b32 v7, v135, v249
	v_cmp_gt_i32_e64 s[0:1], s67, v132
	v_lshl_or_b32 v8, v132, 4, s26
	v_lshlrev_b32_e32 v8, 2, v8
	s_and_b64 s[24:25], vcc, s[0:1]
	s_and_saveexec_b64 s[0:1], s[24:25]
	s_waitcnt lgkmcnt(7)
	v_add_f32_e32 v242, v242, v0
	global_store_dword v8, v242, s[4:5] sc1
	s_mov_b64 exec, s[0:1]
	v_or_b32_e32 v128, 16, v132
	v_cmp_gt_i32_e64 s[0:1], s67, v128
	v_lshl_or_b32 v9, v128, 4, s26
	v_lshlrev_b32_e32 v9, 2, v9
	s_and_b64 s[24:25], vcc, s[0:1]
	s_and_saveexec_b64 s[0:1], s[24:25]
	s_waitcnt lgkmcnt(6)
	v_add_f32_e32 v243, v243, v1
	global_store_dword v9, v243, s[4:5] sc1
	s_mov_b64 exec, s[0:1]
	v_or_b32_e32 v128, 32, v132
	v_cmp_gt_i32_e64 s[0:1], s67, v128
	v_lshl_or_b32 v10, v128, 4, s26
	v_lshlrev_b32_e32 v10, 2, v10
	s_and_b64 s[24:25], vcc, s[0:1]
	s_and_saveexec_b64 s[0:1], s[24:25]
	s_waitcnt lgkmcnt(5)
	v_add_f32_e32 v244, v244, v2
	global_store_dword v10, v244, s[4:5] sc1
	s_mov_b64 exec, s[0:1]
	v_or_b32_e32 v128, 48, v132
	v_cmp_gt_i32_e64 s[0:1], s67, v128
	v_lshl_or_b32 v11, v128, 4, s26
	v_lshlrev_b32_e32 v11, 2, v11
	s_and_b64 s[24:25], vcc, s[0:1]
	s_and_saveexec_b64 s[0:1], s[24:25]
	s_waitcnt lgkmcnt(4)
	v_add_f32_e32 v245, v245, v3
	global_store_dword v11, v245, s[4:5] sc1
	s_mov_b64 exec, s[0:1]
	v_add_u32_e32 v128, 0x80, v132
	v_cmp_gt_i32_e64 s[0:1], s67, v128
	v_lshl_or_b32 v12, v128, 4, s26
	v_lshlrev_b32_e32 v12, 2, v12
	s_and_b64 s[24:25], vcc, s[0:1]
	s_and_saveexec_b64 s[0:1], s[24:25]
	s_waitcnt lgkmcnt(3)
	v_add_f32_e32 v246, v246, v4
	global_store_dword v12, v246, s[4:5] sc1
	s_mov_b64 exec, s[0:1]
	v_add_u32_e32 v128, 0x90, v132
	v_cmp_gt_i32_e64 s[0:1], s67, v128
	v_lshl_or_b32 v13, v128, 4, s26
	v_lshlrev_b32_e32 v13, 2, v13
	s_and_b64 s[24:25], vcc, s[0:1]
	s_and_saveexec_b64 s[0:1], s[24:25]
	s_waitcnt lgkmcnt(2)
	v_add_f32_e32 v247, v247, v5
	global_store_dword v13, v247, s[4:5] sc1
	s_mov_b64 exec, s[0:1]
	v_add_u32_e32 v128, 0xa0, v132
	v_cmp_gt_i32_e64 s[0:1], s67, v128
	v_lshl_or_b32 v14, v128, 4, s26
	v_lshlrev_b32_e32 v14, 2, v14
	s_and_b64 s[24:25], vcc, s[0:1]
	s_and_saveexec_b64 s[0:1], s[24:25]
	s_waitcnt lgkmcnt(1)
	v_add_f32_e32 v248, v248, v6
	global_store_dword v14, v248, s[4:5] sc1
	s_mov_b64 exec, s[0:1]
	v_add_u32_e32 v128, 0xb0, v132
	v_cmp_gt_i32_e64 s[0:1], s67, v128
	v_lshl_or_b32 v15, v128, 4, s26
	v_lshlrev_b32_e32 v15, 2, v15
	s_and_b64 s[24:25], vcc, s[0:1]
	s_and_saveexec_b64 s[0:1], s[24:25]
	s_waitcnt lgkmcnt(0)
	v_add_f32_e32 v249, v249, v7
	global_store_dword v15, v249, s[4:5] sc1
	s_mov_b64 exec, s[0:1]
	s_waitcnt vmcnt(0)
	s_barrier
	v_mbcnt_lo_u32_b32 v0, -1, 0
	v_mbcnt_hi_u32_b32 v0, -1, v0
	s_nop 0
	v_or_b32_e32 v0, s97, v0
	v_cmp_eq_u32_e32 vcc, 0, v0
	s_and_saveexec_b64 s[0:1], vcc
	s_xor_b64 s[0:1], exec, s[0:1]
	s_cbranch_execz .LBB0_1293
	s_mov_b64 s[24:25], exec
	v_mbcnt_lo_u32_b32 v0, s24, 0
	v_mbcnt_hi_u32_b32 v0, s25, v0
	v_cmp_eq_u32_e32 vcc, 0, v0
	s_and_saveexec_b64 s[26:27], vcc
	s_xor_b64 s[26:27], exec, s[26:27]
	s_cbranch_execz .LBB0_1292
	s_lshl_b32 s18, s18, 6
	s_lshl_b64 s[28:29], s[18:19], 2
	s_add_u32 s28, s58, s28
	s_addc_u32 s29, s59, s29
	s_bcnt1_i32_b64 s18, s[24:25]
	v_mov_b32_e32 v0, s18
	global_atomic_add v129, v0, s[28:29]
	s_branch .LBB0_1292
